# attention inner loop rewritten by hand: software-pipelined QK/exp/PV across S-blocks, 3-slot LDS ring, Q kept in registers
# speedup vs baseline: 1.0149x; 1.0149x over previous
; #define LAS __attribute__((address_space(3)))
; __device__ __forceinline__ void attn_unit(const bf16_t* Q, const bf16_t* K, const bf16_t* Vt, int ntiles, int nrows, bf16_t* O, float negM, LAS unsigned char* lds, int tid) {
;     const int lane = tid & 63, w = tid >> 6, r32 = lane & 31, hi = lane >> 5;
;     const int row0 = w * 64 + r32, row1 = row0 + 32;
;     bf16x8 qa[4], qb[4];
;     {
;         const bf16_t* qp0 = Q + (size_t)min(row0, nrows - 1) * 64 + hi * 8;
;         const bf16_t* qp1 = Q + (size_t)min(row1, nrows - 1) * 64 + hi * 8;
; #pragma unroll
;         for (int s = 0; s < 4; ++s) { qa[s] = *(const bf16x8*)(qp0 + 16 * s); qb[s] = *(const bf16x8*)(qp1 + 16 * s); }
;     }
;     LAS unsigned char* qlds = lds + 40960 + w * 4096 + lane * 16;
; #pragma unroll
;     for (int s = 0; s < 4; ++s) *(LAS bf16x8*)(qlds + s * 1024) = qb[s];
;     f32x16 oa0, oa1, ob0, ob1;
; #pragma unroll
;     for (int e = 0; e < 16; ++e) { oa0[e] = 0.f; oa1[e] = 0.f; ob0[e] = 0.f; ob1[e] = 0.f; }
;     float lsa = 0.f, lsb = 0.f;
;     const int srow = tid >> 3, sch = tid & 7;
;     const bf16_t* kg = K + srow * 64 + sch * 8;
;     const bf16_t* vg = Vt + (size_t)srow * TKV + sch * 8;
;     const int soff = srow * 144 + sch * 16;
;     u32x4 kr = *(const u32x4*)kg, vr = *(const u32x4*)vg;
;     *(LAS u32x4*)(lds + soff) = kr; *(LAS u32x4*)(lds + 9216 + soff) = vr;
;     __syncthreads();
;     const int foff = r32 * 144 + hi * 16;
.LBB0_478:
	s_add_i32 s4, s7, 0xfffffe00
	s_cmpk_lt_i32 s7, 0x200
	s_cselect_b64 s[0:1], -1, 0
	s_and_b64 s[0:1], s[0:1], exec
	s_cselect_b32 s4, s7, s4
	s_cselect_b32 s8, s14, 0x100
	s_cselect_b32 s13, 0x44, 4
	s_lshl_b32 s0, s4, 9
	s_and_b32 s9, s0, 0xe00
	s_or_b32 s5, s9, 0x100
	s_cmpk_lt_i32 s7, 0x200
	s_cselect_b64 s[0:1], -1, 0
	s_and_b64 s[0:1], s[0:1], exec
	s_cselect_b32 s28, s5, 0
	s_ashr_i32 s10, s4, 3
	s_cmpk_lt_i32 s7, 0x200
	s_cselect_b64 s[0:1], -1, 0
	s_and_b64 s[0:1], s[0:1], exec
	s_cselect_b32 s29, s10, s7
	s_ashr_i32 s12, s7, 6
	s_cmpk_lt_i32 s7, 0x200
	s_cselect_b64 s[0:1], -1, 0
	s_and_b64 s[4:5], s[0:1], exec
	s_cselect_b32 s5, s12, s10
	s_and_b32 s11, s29, 7
	s_bfe_u32 s4, s29, 0x10002
	s_lshl_b32 s29, s5, 3
	s_or_b32 s29, s29, s11
	s_mul_hi_i32 s30, s29, 0x1100
	s_mulk_i32 s29, 0x1100
	s_add_u32 s28, s29, s28
	s_addc_u32 s29, s30, 0
	s_lshl_b64 s[28:29], s[28:29], 7
	s_add_u32 s28, s34, s28
	s_addc_u32 s29, s35, s29
	s_add_i32 s31, s8, -1
	v_min_i32_e32 v16, s31, v170
	v_ashrrev_i32_e32 v17, 31, v16
	v_lshlrev_b64 v[16:17], 7, v[16:17]
	v_lshl_add_u64 v[16:17], s[28:29], 0, v[16:17]
	v_lshl_add_u64 v[28:29], v[16:17], 0, v[186:187]
	v_min_i32_e32 v16, s31, v172
	v_ashrrev_i32_e32 v17, 31, v16
	v_lshlrev_b64 v[16:17], 7, v[16:17]
	v_lshl_add_u64 v[16:17], s[28:29], 0, v[16:17]
	v_lshl_add_u64 v[30:31], v[16:17], 0, v[186:187]
	global_load_dwordx4 v[146:149], v[28:29], off
	global_load_dwordx4 v[150:153], v[28:29], off offset:32
	global_load_dwordx4 v[154:157], v[28:29], off offset:64
	global_load_dwordx4 v[158:161], v[28:29], off offset:96
	global_load_dwordx4 v[96:99], v[30:31], off
	global_load_dwordx4 v[100:103], v[30:31], off offset:32
	global_load_dwordx4 v[104:107], v[30:31], off offset:64
	global_load_dwordx4 v[108:111], v[30:31], off offset:96
	s_lshl_b32 s5, s5, 1
	s_or_b32 s30, s4, s5
	v_mad_i64_i32 v[112:113], s[28:29], s30, v233, v[174:175]
	v_mad_i64_i32 v[114:115], s[28:29], s30, v233, v[176:177]
	global_load_dwordx4 v[162:165], v[112:113], off
	global_load_dwordx4 v[166:169], v[114:115], off
	v_mad_i64_i32 v[196:197], s[4:5], s30, v233, v[184:185]
	v_mad_i64_i32 v[198:199], s[4:5], s30, v233, v[192:193]
	v_mov_b32_e32 v173, v181
	s_movk_i32 s28, 0x4800
	v_add_u32_e32 v188, s28, v181
	s_mov_b32 s29, 0
	v_mov_b32_e32 v194, 0
	v_mov_b32_e32 v195, 0
	v_mov_b32_e32 v226, 0
	v_mov_b32_e32 v227, 0
	v_mov_b32_e32 v16, 0
	v_mov_b32_e32 v17, 0
	v_mov_b32_e32 v18, 0
	v_mov_b32_e32 v19, 0
	v_mov_b32_e32 v20, 0
	v_mov_b32_e32 v21, 0
	v_mov_b32_e32 v22, 0
	v_mov_b32_e32 v23, 0
	v_mov_b32_e32 v24, 0
	v_mov_b32_e32 v25, 0
	v_mov_b32_e32 v26, 0
	v_mov_b32_e32 v27, 0
	v_mov_b32_e32 v28, 0
	v_mov_b32_e32 v29, 0
	v_mov_b32_e32 v30, 0
	v_mov_b32_e32 v31, 0
	v_mov_b32_e32 v32, 0
	v_mov_b32_e32 v33, 0
	v_mov_b32_e32 v34, 0
	v_mov_b32_e32 v35, 0
	v_mov_b32_e32 v36, 0
	v_mov_b32_e32 v37, 0
	v_mov_b32_e32 v38, 0
	v_mov_b32_e32 v39, 0
	v_mov_b32_e32 v40, 0
	v_mov_b32_e32 v41, 0
	v_mov_b32_e32 v42, 0
	v_mov_b32_e32 v43, 0
	v_mov_b32_e32 v44, 0
	v_mov_b32_e32 v45, 0
	v_mov_b32_e32 v46, 0
	v_mov_b32_e32 v47, 0
	v_mov_b32_e32 v48, 0
	v_mov_b32_e32 v49, 0
	v_mov_b32_e32 v50, 0
	v_mov_b32_e32 v51, 0
	v_mov_b32_e32 v52, 0
	v_mov_b32_e32 v53, 0
	v_mov_b32_e32 v54, 0
	v_mov_b32_e32 v55, 0
	v_mov_b32_e32 v56, 0
	v_mov_b32_e32 v57, 0
	v_mov_b32_e32 v58, 0
	v_mov_b32_e32 v59, 0
	v_mov_b32_e32 v60, 0
	v_mov_b32_e32 v61, 0
	v_mov_b32_e32 v62, 0
	v_mov_b32_e32 v63, 0
	v_mov_b32_e32 v64, 0
	v_mov_b32_e32 v65, 0
	v_mov_b32_e32 v66, 0
	v_mov_b32_e32 v67, 0
	v_mov_b32_e32 v68, 0
	v_mov_b32_e32 v69, 0
	v_mov_b32_e32 v70, 0
	v_mov_b32_e32 v71, 0
	v_mov_b32_e32 v72, 0
	v_mov_b32_e32 v73, 0
	v_mov_b32_e32 v74, 0
	v_mov_b32_e32 v75, 0
	v_mov_b32_e32 v76, 0
	v_mov_b32_e32 v77, 0
	v_mov_b32_e32 v78, 0
	v_mov_b32_e32 v79, 0
	v_mov_b32_e32 v238, 0
	v_mov_b32_e32 v239, 0
	v_mov_b32_e32 v240, 0
	v_mov_b32_e32 v241, 0
	v_mov_b32_e32 v242, 0
	v_mov_b32_e32 v243, 0
	v_mov_b32_e32 v244, 0
	v_mov_b32_e32 v245, 0
	s_waitcnt vmcnt(0)
	ds_write_b128 v145, v[162:165]
	ds_write_b128 v145, v[166:169] offset:9216
	global_load_dwordx4 v[162:165], v[198:199], off
	global_load_dwordx4 v[166:169], v[196:197], off
	v_lshl_add_u64 v[198:199], v[198:199], 0, s[80:81]
	v_lshl_add_u64 v[196:197], v[196:197], 0, s[44:45]
	s_waitcnt lgkmcnt(0)
	s_barrier
	ds_read_b128 v[80:83], v173
	ds_read_b128 v[84:87], v173 offset:32
	ds_read_b128 v[88:91], v173 offset:64
	ds_read_b128 v[92:95], v173 offset:96
	ds_read_b128 v[200:203], v173 offset:9280
	ds_read_b128 v[204:207], v173 offset:13888
	ds_read_b128 v[208:211], v173 offset:9312
	ds_read_b128 v[212:215], v173 offset:13920
	s_waitcnt lgkmcnt(7)
	v_mfma_f32_32x32x16_bf16 v[112:127], v[80:83], v[146:149], v[0:15]
	s_waitcnt lgkmcnt(6)
	v_mfma_f32_32x32x16_bf16 v[112:127], v[84:87], v[150:153], v[112:127]
	s_waitcnt lgkmcnt(5)
	v_mfma_f32_32x32x16_bf16 v[112:127], v[88:91], v[154:157], v[112:127]
	s_waitcnt lgkmcnt(4)
	v_mfma_f32_32x32x16_bf16 v[112:127], v[92:95], v[158:161], v[112:127]
	s_waitcnt lgkmcnt(0)
	s_nop 7
	s_nop 3
; #define LAS __attribute__((address_space(3)))
; __device__ __forceinline__ void attn_unit(const bf16_t* Q, const bf16_t* K, const bf16_t* Vt, int ntiles, int nrows, bf16_t* O, float negM, LAS unsigned char* lds, int tid) {
;     ...
;     for (int t = 0; t < ntiles; ++t) {
;         const int cur = t & 1;
;         const bool more = (t + 1 < ntiles);
;         if (more) { kr = *(const u32x4*)(kg + (size_t)(t + 1) * 4096); vr = *(const u32x4*)(vg + (size_t)(t + 1) * 64); }
;         const LAS unsigned char* kb = lds + cur * 18432 + foff;
;         const LAS unsigned char* vb = kb + 9216;
;         bf16x8 kf0[4], kf1[4];
; #pragma unroll
;         for (int s = 0; s < 4; ++s) { kf0[s] = *(const LAS bf16x8*)(kb + s * 32); kf1[s] = *(const LAS bf16x8*)(kb + 32 * 144 + s * 32); }
;         bf16x8 pa[4], pb[4];
;         ATT_SCORES(qa, pa, lsa);
;         bf16x8 qc[4];
; #pragma unroll
;         for (int s = 0; s < 4; ++s) qc[s] = *(const LAS bf16x8*)(qlds + s * 1024);
;         ATT_SCORES(qc, pb, lsb);
; #pragma unroll
;         for (int s = 0; s < 4; ++s) {
;             const bf16x8 v0 = *(const LAS bf16x8*)(vb + s * 32), v1 = *(const LAS bf16x8*)(vb + 32 * 144 + s * 32);
;             oa0 = __builtin_amdgcn_mfma_f32_32x32x16_bf16(v0, pa[s], oa0, 0, 0, 0);
;             oa1 = __builtin_amdgcn_mfma_f32_32x32x16_bf16(v1, pa[s], oa1, 0, 0, 0);
;             ob0 = __builtin_amdgcn_mfma_f32_32x32x16_bf16(v0, pb[s], ob0, 0, 0, 0);
;             ob1 = __builtin_amdgcn_mfma_f32_32x32x16_bf16(v1, pb[s], ob1, 0, 0, 0);
;         }
;         if (more) { *(LAS u32x4*)(lds + (cur ^ 1) * 18432 + soff) = kr; *(LAS u32x4*)(lds + (cur ^ 1) * 18432 + 9216 + soff) = vr; }
.Lattn_tile:
	v_mfma_f32_32x32x16_bf16 v[128:143], v[80:83], v[96:99], v[0:15]
	ds_read_b128 v[80:83], v173 offset:4608
	v_exp_f32_e32 v112, v112
	v_exp_f32_e32 v113, v113
	v_mfma_f32_32x32x16_bf16 v[16:31], v[200:203], v[238:241], v[16:31]
	ds_read_b128 v[200:203], v173 offset:9216
	v_exp_f32_e32 v114, v114
	v_exp_f32_e32 v115, v115
	v_cvt_pk_bf16_f32 v216, v112, v113
	v_add_f32_e32 v194, v194, v112
	v_add_f32_e32 v226, v226, v113
	v_mfma_f32_32x32x16_bf16 v[128:143], v[84:87], v[100:103], v[128:143]
	ds_read_b128 v[84:87], v173 offset:4640
	v_exp_f32_e32 v116, v116
	v_exp_f32_e32 v117, v117
	v_cvt_pk_bf16_f32 v217, v114, v115
	v_add_f32_e32 v194, v194, v114
	v_add_f32_e32 v226, v226, v115
	v_mfma_f32_32x32x16_bf16 v[32:47], v[204:207], v[238:241], v[32:47]
	ds_read_b128 v[204:207], v173 offset:13824
	v_exp_f32_e32 v118, v118
	v_exp_f32_e32 v119, v119
	v_cvt_pk_bf16_f32 v218, v116, v117
	v_add_f32_e32 v194, v194, v116
	v_add_f32_e32 v226, v226, v117
	v_mfma_f32_32x32x16_bf16 v[128:143], v[88:91], v[104:107], v[128:143]
	ds_read_b128 v[88:91], v173 offset:4672
	v_exp_f32_e32 v120, v120
	v_exp_f32_e32 v121, v121
	v_cvt_pk_bf16_f32 v219, v118, v119
	v_add_f32_e32 v194, v194, v118
	v_add_f32_e32 v226, v226, v119
	v_mfma_f32_32x32x16_bf16 v[16:31], v[208:211], v[242:245], v[16:31]
	ds_read_b128 v[208:211], v173 offset:9248
	v_exp_f32_e32 v122, v122
	v_exp_f32_e32 v123, v123
	v_cvt_pk_bf16_f32 v234, v120, v121
	v_add_f32_e32 v194, v194, v120
	v_add_f32_e32 v226, v226, v121
	v_mfma_f32_32x32x16_bf16 v[128:143], v[92:95], v[108:111], v[128:143]
	ds_read_b128 v[92:95], v173 offset:4704
	v_exp_f32_e32 v124, v124
	v_exp_f32_e32 v125, v125
	v_cvt_pk_bf16_f32 v235, v122, v123
	v_add_f32_e32 v194, v194, v122
	v_add_f32_e32 v226, v226, v123
	v_mfma_f32_32x32x16_bf16 v[32:47], v[212:215], v[242:245], v[32:47]
	ds_read_b128 v[212:215], v173 offset:13856
	v_exp_f32_e32 v126, v126
	v_exp_f32_e32 v127, v127
	v_cvt_pk_bf16_f32 v236, v124, v125
	v_add_f32_e32 v194, v194, v124
	v_add_f32_e32 v226, v226, v125
	v_cvt_pk_bf16_f32 v237, v126, v127
	v_add_f32_e32 v194, v194, v126
	v_add_f32_e32 v226, v226, v127
	s_waitcnt vmcnt(0)
	v_add_u32_e32 v189, s28, v145
	ds_write_b128 v189, v[162:165]
	ds_write_b128 v189, v[166:169] offset:9216
	s_waitcnt lgkmcnt(9)
	v_mfma_f32_32x32x16_bf16 v[112:127], v[80:83], v[146:149], v[0:15]
	v_exp_f32_e32 v128, v128
	v_exp_f32_e32 v129, v129
	s_waitcnt lgkmcnt(8)
	v_mfma_f32_32x32x16_bf16 v[48:63], v[200:203], v[216:219], v[48:63]
	v_exp_f32_e32 v130, v130
	v_exp_f32_e32 v131, v131
	v_cvt_pk_bf16_f32 v238, v128, v129
	v_add_f32_e32 v195, v195, v128
	v_add_f32_e32 v227, v227, v129
	s_waitcnt lgkmcnt(7)
	v_mfma_f32_32x32x16_bf16 v[112:127], v[84:87], v[150:153], v[112:127]
	v_exp_f32_e32 v132, v132
	v_exp_f32_e32 v133, v133
	v_cvt_pk_bf16_f32 v239, v130, v131
	v_add_f32_e32 v195, v195, v130
	v_add_f32_e32 v227, v227, v131
	s_waitcnt lgkmcnt(6)
	v_mfma_f32_32x32x16_bf16 v[64:79], v[204:207], v[216:219], v[64:79]
	v_exp_f32_e32 v134, v134
	v_exp_f32_e32 v135, v135
	v_cvt_pk_bf16_f32 v240, v132, v133
	v_add_f32_e32 v195, v195, v132
	v_add_f32_e32 v227, v227, v133
	s_waitcnt lgkmcnt(5)
	v_mfma_f32_32x32x16_bf16 v[112:127], v[88:91], v[154:157], v[112:127]
	v_exp_f32_e32 v136, v136
	v_exp_f32_e32 v137, v137
	v_cvt_pk_bf16_f32 v241, v134, v135
	v_add_f32_e32 v195, v195, v134
	v_add_f32_e32 v227, v227, v135
	s_waitcnt lgkmcnt(4)
	v_mfma_f32_32x32x16_bf16 v[48:63], v[208:211], v[234:237], v[48:63]
	v_exp_f32_e32 v138, v138
	v_exp_f32_e32 v139, v139
	v_cvt_pk_bf16_f32 v242, v136, v137
	v_add_f32_e32 v195, v195, v136
	v_add_f32_e32 v227, v227, v137
	s_waitcnt lgkmcnt(3)
	v_mfma_f32_32x32x16_bf16 v[112:127], v[92:95], v[158:161], v[112:127]
	v_exp_f32_e32 v140, v140
	v_exp_f32_e32 v141, v141
	v_cvt_pk_bf16_f32 v243, v138, v139
	v_add_f32_e32 v195, v195, v138
	v_add_f32_e32 v227, v227, v139
	s_waitcnt lgkmcnt(2)
	v_mfma_f32_32x32x16_bf16 v[64:79], v[212:215], v[234:237], v[64:79]
	v_exp_f32_e32 v142, v142
	v_exp_f32_e32 v143, v143
	v_cvt_pk_bf16_f32 v244, v140, v141
	v_add_f32_e32 v195, v195, v140
	v_add_f32_e32 v227, v227, v141
	v_cvt_pk_bf16_f32 v245, v142, v143
	v_add_f32_e32 v195, v195, v142
	v_add_f32_e32 v227, v227, v143
	s_waitcnt lgkmcnt(0)
	s_barrier
; #define LAS __attribute__((address_space(3)))
; __device__ __forceinline__ void attn_unit(const bf16_t* Q, const bf16_t* K, const bf16_t* Vt, int ntiles, int nrows, bf16_t* O, float negM, LAS unsigned char* lds, int tid) {
;     ...
;     for (int t = 0; t < ntiles; ++t) {
;         const int cur = t & 1;
;         const bool more = (t + 1 < ntiles);
;         if (more) { kr = *(const u32x4*)(kg + (size_t)(t + 1) * 4096); vr = *(const u32x4*)(vg + (size_t)(t + 1) * 64); }
;         const LAS unsigned char* kb = lds + cur * 18432 + foff;
;         const LAS unsigned char* vb = kb + 9216;
;         bf16x8 kf0[4], kf1[4];
; #pragma unroll
;         for (int s = 0; s < 4; ++s) { kf0[s] = *(const LAS bf16x8*)(kb + s * 32); kf1[s] = *(const LAS bf16x8*)(kb + 32 * 144 + s * 32); }
;         bf16x8 pa[4], pb[4];
;         ATT_SCORES(qa, pa, lsa);
;         bf16x8 qc[4];
; #pragma unroll
;         for (int s = 0; s < 4; ++s) qc[s] = *(const LAS bf16x8*)(qlds + s * 1024);
;         ATT_SCORES(qc, pb, lsb);
; #pragma unroll
;         for (int s = 0; s < 4; ++s) {
;             const bf16x8 v0 = *(const LAS bf16x8*)(vb + s * 32), v1 = *(const LAS bf16x8*)(vb + 32 * 144 + s * 32);
;             oa0 = __builtin_amdgcn_mfma_f32_32x32x16_bf16(v0, pa[s], oa0, 0, 0, 0);
;             oa1 = __builtin_amdgcn_mfma_f32_32x32x16_bf16(v1, pa[s], oa1, 0, 0, 0);
;             ob0 = __builtin_amdgcn_mfma_f32_32x32x16_bf16(v0, pb[s], ob0, 0, 0, 0);
;             ob1 = __builtin_amdgcn_mfma_f32_32x32x16_bf16(v1, pb[s], ob1, 0, 0, 0);
;         }
;         if (more) { *(LAS u32x4*)(lds + (cur ^ 1) * 18432 + soff) = kr; *(LAS u32x4*)(lds + (cur ^ 1) * 18432 + 9216 + soff) = vr; }
;         __syncthreads();
;     }
	global_load_dwordx4 v[162:165], v[198:199], off
	global_load_dwordx4 v[166:169], v[196:197], off
	v_lshl_add_u64 v[198:199], v[198:199], 0, s[80:81]
	v_lshl_add_u64 v[196:197], v[196:197], 0, s[44:45]
	v_mfma_f32_32x32x16_bf16 v[128:143], v[80:83], v[96:99], v[0:15]
	ds_read_b128 v[80:83], v188
	v_exp_f32_e32 v112, v112
	v_exp_f32_e32 v113, v113
	v_mfma_f32_32x32x16_bf16 v[16:31], v[200:203], v[238:241], v[16:31]
	ds_read_b128 v[200:203], v173 offset:9280
	v_exp_f32_e32 v114, v114
	v_exp_f32_e32 v115, v115
	v_cvt_pk_bf16_f32 v216, v112, v113
	v_add_f32_e32 v194, v194, v112
	v_add_f32_e32 v226, v226, v113
	v_mfma_f32_32x32x16_bf16 v[128:143], v[84:87], v[100:103], v[128:143]
	ds_read_b128 v[84:87], v188 offset:32
	v_exp_f32_e32 v116, v116
	v_exp_f32_e32 v117, v117
	v_cvt_pk_bf16_f32 v217, v114, v115
	v_add_f32_e32 v194, v194, v114
	v_add_f32_e32 v226, v226, v115
	v_mfma_f32_32x32x16_bf16 v[32:47], v[204:207], v[238:241], v[32:47]
	ds_read_b128 v[204:207], v173 offset:13888
	v_exp_f32_e32 v118, v118
	v_exp_f32_e32 v119, v119
	v_cvt_pk_bf16_f32 v218, v116, v117
	v_add_f32_e32 v194, v194, v116
	v_add_f32_e32 v226, v226, v117
	v_mfma_f32_32x32x16_bf16 v[128:143], v[88:91], v[104:107], v[128:143]
	ds_read_b128 v[88:91], v188 offset:64
	v_exp_f32_e32 v120, v120
	v_exp_f32_e32 v121, v121
	v_cvt_pk_bf16_f32 v219, v118, v119
	v_add_f32_e32 v194, v194, v118
	v_add_f32_e32 v226, v226, v119
	v_mfma_f32_32x32x16_bf16 v[16:31], v[208:211], v[242:245], v[16:31]
	ds_read_b128 v[208:211], v173 offset:9312
	v_exp_f32_e32 v122, v122
	v_exp_f32_e32 v123, v123
	v_cvt_pk_bf16_f32 v234, v120, v121
	v_add_f32_e32 v194, v194, v120
	v_add_f32_e32 v226, v226, v121
	v_mfma_f32_32x32x16_bf16 v[128:143], v[92:95], v[108:111], v[128:143]
	ds_read_b128 v[92:95], v188 offset:96
	v_exp_f32_e32 v124, v124
	v_exp_f32_e32 v125, v125
	v_cvt_pk_bf16_f32 v235, v122, v123
	v_add_f32_e32 v194, v194, v122
	v_add_f32_e32 v226, v226, v123
	v_mfma_f32_32x32x16_bf16 v[32:47], v[212:215], v[242:245], v[32:47]
	ds_read_b128 v[212:215], v173 offset:13920
	v_exp_f32_e32 v126, v126
	v_exp_f32_e32 v127, v127
	v_cvt_pk_bf16_f32 v236, v124, v125
	v_add_f32_e32 v194, v194, v124
	v_add_f32_e32 v226, v226, v125
	v_cvt_pk_bf16_f32 v237, v126, v127
	v_add_f32_e32 v194, v194, v126
	v_add_f32_e32 v226, v226, v127
	s_waitcnt lgkmcnt(7)
	v_mfma_f32_32x32x16_bf16 v[112:127], v[80:83], v[146:149], v[0:15]
	v_exp_f32_e32 v128, v128
	v_exp_f32_e32 v129, v129
	s_waitcnt lgkmcnt(6)
	v_mfma_f32_32x32x16_bf16 v[48:63], v[200:203], v[216:219], v[48:63]
	v_exp_f32_e32 v130, v130
	v_exp_f32_e32 v131, v131
	v_cvt_pk_bf16_f32 v238, v128, v129
	v_add_f32_e32 v195, v195, v128
	v_add_f32_e32 v227, v227, v129
	s_waitcnt lgkmcnt(5)
	v_mfma_f32_32x32x16_bf16 v[112:127], v[84:87], v[150:153], v[112:127]
	v_exp_f32_e32 v132, v132
	v_exp_f32_e32 v133, v133
	v_cvt_pk_bf16_f32 v239, v130, v131
	v_add_f32_e32 v195, v195, v130
	v_add_f32_e32 v227, v227, v131
	s_waitcnt lgkmcnt(4)
	v_mfma_f32_32x32x16_bf16 v[64:79], v[204:207], v[216:219], v[64:79]
	v_exp_f32_e32 v134, v134
	v_exp_f32_e32 v135, v135
	v_cvt_pk_bf16_f32 v240, v132, v133
	v_add_f32_e32 v195, v195, v132
	v_add_f32_e32 v227, v227, v133
	s_waitcnt lgkmcnt(3)
	v_mfma_f32_32x32x16_bf16 v[112:127], v[88:91], v[154:157], v[112:127]
	v_exp_f32_e32 v136, v136
	v_exp_f32_e32 v137, v137
	v_cvt_pk_bf16_f32 v241, v134, v135
	v_add_f32_e32 v195, v195, v134
	v_add_f32_e32 v227, v227, v135
	s_waitcnt lgkmcnt(2)
	v_mfma_f32_32x32x16_bf16 v[48:63], v[208:211], v[234:237], v[48:63]
	v_exp_f32_e32 v138, v138
	v_exp_f32_e32 v139, v139
	v_cvt_pk_bf16_f32 v242, v136, v137
	v_add_f32_e32 v195, v195, v136
	v_add_f32_e32 v227, v227, v137
	s_waitcnt lgkmcnt(1)
	v_mfma_f32_32x32x16_bf16 v[112:127], v[92:95], v[158:161], v[112:127]
	v_exp_f32_e32 v140, v140
	v_exp_f32_e32 v141, v141
	v_cvt_pk_bf16_f32 v243, v138, v139
	v_add_f32_e32 v195, v195, v138
	v_add_f32_e32 v227, v227, v139
	s_waitcnt lgkmcnt(0)
	v_mfma_f32_32x32x16_bf16 v[64:79], v[212:215], v[234:237], v[64:79]
	v_exp_f32_e32 v142, v142
	v_exp_f32_e32 v143, v143
	v_cvt_pk_bf16_f32 v244, v140, v141
	v_add_f32_e32 v195, v195, v140
	v_add_f32_e32 v227, v227, v141
	v_cvt_pk_bf16_f32 v245, v142, v143
	v_add_f32_e32 v195, v195, v142
	v_add_f32_e32 v227, v227, v143
	v_mov_b32_e32 v173, v188
	s_add_i32 s28, s28, 0x4800
	s_cmp_eq_u32 s28, 0xd800
	s_cselect_b32 s28, 0, s28
	v_add_u32_e32 v188, s28, v181
	s_add_i32 s29, s29, 1
	s_cmp_lt_i32 s29, s13
	s_cbranch_scc1 .Lattn_tile
	s_waitcnt lgkmcnt(0)
	s_barrier
	v_mfma_f32_32x32x16_bf16 v[16:31], v[200:203], v[238:241], v[16:31]
	v_mfma_f32_32x32x16_bf16 v[32:47], v[204:207], v[238:241], v[32:47]
	v_mfma_f32_32x32x16_bf16 v[16:31], v[208:211], v[242:245], v[16:31]
	v_mfma_f32_32x32x16_bf16 v[32:47], v[212:215], v[242:245], v[32:47]
	v_add_f32_e32 v194, v194, v226
	v_add_f32_e32 v195, v195, v227
	s_nop 7
	s_nop 3
